# P1 main K-loop flattened: never-taken last-K-tile paths and their tests removed (full units always have a successor), one straight-line body with a single back edge
# speedup vs baseline: 1.0015x; 1.0015x over previous
.LBB0_107:
	ds_read_b128 v[150:153], v248
	ds_read_b128 v[154:157], v248 offset:1024
	ds_read_b128 v[158:161], v248 offset:2048
	ds_read_b128 v[162:165], v248 offset:3072
	ds_read_b128 v[134:137], v249
	ds_read_b128 v[138:141], v249 offset:1024
	ds_read_b128 v[142:145], v249 offset:2048
	ds_read_b128 v[146:149], v249 offset:3072
	s_mov_b64 s[0:1], s[76:77]
	s_add_u32 s76, s0, 0x100
	s_addc_u32 s77, s1, 0
	s_cmp_lg_u32 s45, 12
	s_cselect_b64 s[88:89], -1, 0
	s_and_b64 s[2:3], s[88:89], exec
	s_cselect_b32 s3, s44, s63
	s_cselect_b32 s2, s36, s65
	s_cselect_b32 s85, s77, s4
	s_cselect_b32 s84, s76, s43
	v_lshl_add_u64 v[4:5], s[0:1], 0, v[214:215]
	s_add_i32 m0, s61, 0xc000
	s_waitcnt lgkmcnt(0)
	ds_read_b128 v[166:169], v250
	ds_read_b128 v[170:173], v250 offset:1024
	ds_read_b128 v[174:177], v250 offset:2048
	ds_read_b128 v[178:181], v250 offset:3072
	ds_read_b128 v[182:185], v250 offset:4096
	ds_read_b128 v[186:189], v250 offset:5120
	ds_read_b128 v[190:193], v250 offset:6144
	ds_read_b128 v[194:197], v250 offset:7168
	global_load_lds_dwordx4 v[4:5], off
	v_lshl_add_u64 v[4:5], s[0:1], 0, v[216:217]
	s_add_i32 m0, s61, 0xe000
	s_nop 0
	global_load_lds_dwordx4 v[4:5], off
	s_waitcnt vmcnt(8)
	s_waitcnt lgkmcnt(0)
	s_setprio 1
	s_barrier
	v_mfma_f32_16x16x32_bf16 v[102:105], v[150:153], v[166:169], v[102:105]
	v_mfma_f32_16x16x32_bf16 v[70:73], v[158:161], v[166:169], v[70:73]
	v_mfma_f32_16x16x32_bf16 v[114:117], v[150:153], v[174:177], v[114:117]
	v_mfma_f32_16x16x32_bf16 v[82:85], v[158:161], v[174:177], v[82:85]
	v_mfma_f32_16x16x32_bf16 v[110:113], v[150:153], v[182:185], v[110:113]
	v_mfma_f32_16x16x32_bf16 v[78:81], v[158:161], v[182:185], v[78:81]
	v_mfma_f32_16x16x32_bf16 v[106:109], v[150:153], v[190:193], v[106:109]
	v_mfma_f32_16x16x32_bf16 v[74:77], v[158:161], v[190:193], v[74:77]
	v_mfma_f32_16x16x32_bf16 v[102:105], v[154:157], v[170:173], v[102:105]
	v_mfma_f32_16x16x32_bf16 v[70:73], v[162:165], v[170:173], v[70:73]
	v_mfma_f32_16x16x32_bf16 v[114:117], v[154:157], v[178:181], v[114:117]
	v_mfma_f32_16x16x32_bf16 v[82:85], v[162:165], v[178:181], v[82:85]
	v_mfma_f32_16x16x32_bf16 v[110:113], v[154:157], v[186:189], v[110:113]
	v_mfma_f32_16x16x32_bf16 v[78:81], v[162:165], v[186:189], v[78:81]
	v_mfma_f32_16x16x32_bf16 v[106:109], v[154:157], v[194:197], v[106:109]
	v_mfma_f32_16x16x32_bf16 v[74:77], v[162:165], v[194:197], v[74:77]
	v_mfma_f32_16x16x32_bf16 v[130:133], v[134:137], v[166:169], v[130:133]
	v_mfma_f32_16x16x32_bf16 v[98:101], v[142:145], v[166:169], v[98:101]
	v_mfma_f32_16x16x32_bf16 v[126:129], v[134:137], v[174:177], v[126:129]
	v_mfma_f32_16x16x32_bf16 v[94:97], v[142:145], v[174:177], v[94:97]
	v_mfma_f32_16x16x32_bf16 v[122:125], v[134:137], v[182:185], v[122:125]
	v_mfma_f32_16x16x32_bf16 v[90:93], v[142:145], v[182:185], v[90:93]
	v_mfma_f32_16x16x32_bf16 v[118:121], v[134:137], v[190:193], v[118:121]
	v_mfma_f32_16x16x32_bf16 v[86:89], v[142:145], v[190:193], v[86:89]
	v_mfma_f32_16x16x32_bf16 v[130:133], v[138:141], v[170:173], v[130:133]
	v_mfma_f32_16x16x32_bf16 v[98:101], v[146:149], v[170:173], v[98:101]
	v_mfma_f32_16x16x32_bf16 v[126:129], v[138:141], v[178:181], v[126:129]
	v_mfma_f32_16x16x32_bf16 v[94:97], v[146:149], v[178:181], v[94:97]
	v_mfma_f32_16x16x32_bf16 v[122:125], v[138:141], v[186:189], v[122:125]
	v_mfma_f32_16x16x32_bf16 v[90:93], v[146:149], v[186:189], v[90:93]
	v_mfma_f32_16x16x32_bf16 v[118:121], v[138:141], v[194:197], v[118:121]
	v_mfma_f32_16x16x32_bf16 v[86:89], v[146:149], v[194:197], v[86:89]
	s_setprio 0
	s_barrier
	ds_read_b128 v[190:193], v250 offset:16384
	ds_read_b128 v[194:197], v250 offset:17408
	ds_read_b128 v[182:185], v250 offset:18432
	ds_read_b128 v[186:189], v250 offset:19456
	ds_read_b128 v[174:177], v250 offset:20480
	ds_read_b128 v[178:181], v250 offset:21504
	ds_read_b128 v[166:169], v250 offset:22528
	ds_read_b128 v[170:173], v250 offset:23552
	v_lshl_add_u64 v[224:225], s[2:3], 0, v[208:209]
	v_lshl_add_u64 v[222:223], s[2:3], 0, v[212:213]
	v_lshl_add_u64 v[220:221], s[84:85], 0, v[206:207]
	v_lshl_add_u64 v[4:5], s[84:85], 0, v[210:211]
	s_mov_b32 m0, s73
	s_add_u32 s0, s2, 0x40000
	global_load_lds_dwordx4 v[224:225], off
	s_mov_b32 m0, s75
	s_addc_u32 s1, s3, 0
	global_load_lds_dwordx4 v[222:223], off
	v_lshl_add_u64 v[252:253], s[0:1], 0, v[208:209]
	s_mov_b32 m0, s92
	s_nop 0
	global_load_lds_dwordx4 v[252:253], off
	v_lshl_add_u64 v[252:253], s[0:1], 0, v[212:213]
	s_mov_b32 m0, s93
	s_nop 0
	global_load_lds_dwordx4 v[252:253], off
	s_mov_b32 m0, s61
	s_nop 0
	global_load_lds_dwordx4 v[220:221], off
	s_mov_b32 m0, s94
	s_nop 0
	global_load_lds_dwordx4 v[4:5], off
	s_waitcnt vmcnt(8)
.LBB0_111:
	s_waitcnt lgkmcnt(0)
	s_setprio 1
	s_barrier
	v_mfma_f32_16x16x32_bf16 v[38:41], v[150:153], v[190:193], v[38:41]
	v_mfma_f32_16x16x32_bf16 v[6:9], v[158:161], v[190:193], v[6:9]
	v_mfma_f32_16x16x32_bf16 v[50:53], v[150:153], v[182:185], v[50:53]
	v_mfma_f32_16x16x32_bf16 v[18:21], v[158:161], v[182:185], v[18:21]
	v_mfma_f32_16x16x32_bf16 v[46:49], v[150:153], v[174:177], v[46:49]
	v_mfma_f32_16x16x32_bf16 v[14:17], v[158:161], v[174:177], v[14:17]
	v_mfma_f32_16x16x32_bf16 v[42:45], v[150:153], v[166:169], v[42:45]
	v_mfma_f32_16x16x32_bf16 v[10:13], v[158:161], v[166:169], v[10:13]
	v_mfma_f32_16x16x32_bf16 v[38:41], v[154:157], v[194:197], v[38:41]
	v_mfma_f32_16x16x32_bf16 v[6:9], v[162:165], v[194:197], v[6:9]
	v_mfma_f32_16x16x32_bf16 v[50:53], v[154:157], v[186:189], v[50:53]
	v_mfma_f32_16x16x32_bf16 v[18:21], v[162:165], v[186:189], v[18:21]
	v_mfma_f32_16x16x32_bf16 v[46:49], v[154:157], v[178:181], v[46:49]
	v_mfma_f32_16x16x32_bf16 v[14:17], v[162:165], v[178:181], v[14:17]
	v_mfma_f32_16x16x32_bf16 v[42:45], v[154:157], v[170:173], v[42:45]
	v_mfma_f32_16x16x32_bf16 v[10:13], v[162:165], v[170:173], v[10:13]
	v_mfma_f32_16x16x32_bf16 v[62:65], v[134:137], v[190:193], v[62:65]
	v_mfma_f32_16x16x32_bf16 v[30:33], v[142:145], v[190:193], v[30:33]
	v_mfma_f32_16x16x32_bf16 v[66:69], v[134:137], v[182:185], v[66:69]
	v_mfma_f32_16x16x32_bf16 v[34:37], v[142:145], v[182:185], v[34:37]
	v_mfma_f32_16x16x32_bf16 v[58:61], v[134:137], v[174:177], v[58:61]
	v_mfma_f32_16x16x32_bf16 v[26:29], v[142:145], v[174:177], v[26:29]
	v_mfma_f32_16x16x32_bf16 v[54:57], v[134:137], v[166:169], v[54:57]
	v_mfma_f32_16x16x32_bf16 v[22:25], v[142:145], v[166:169], v[22:25]
	v_mfma_f32_16x16x32_bf16 v[62:65], v[138:141], v[194:197], v[62:65]
	v_mfma_f32_16x16x32_bf16 v[30:33], v[146:149], v[194:197], v[30:33]
	v_mfma_f32_16x16x32_bf16 v[66:69], v[138:141], v[186:189], v[66:69]
	v_mfma_f32_16x16x32_bf16 v[34:37], v[146:149], v[186:189], v[34:37]
	v_mfma_f32_16x16x32_bf16 v[58:61], v[138:141], v[178:181], v[58:61]
	v_mfma_f32_16x16x32_bf16 v[26:29], v[146:149], v[178:181], v[26:29]
	v_mfma_f32_16x16x32_bf16 v[54:57], v[138:141], v[170:173], v[54:57]
	v_mfma_f32_16x16x32_bf16 v[22:25], v[146:149], v[170:173], v[22:25]
	s_setprio 0
.LBB0_113:
	s_barrier
	v_add_u32_e32 v3, 0x18000, v247
	ds_read_b128 v[150:153], v3
	ds_read_b128 v[154:157], v3 offset:1024
	ds_read_b128 v[158:161], v3 offset:2048
	ds_read_b128 v[162:165], v3 offset:3072
	v_add_u32_e32 v3, 0x1c000, v247
	ds_read_b128 v[134:137], v3
	ds_read_b128 v[138:141], v3 offset:1024
	ds_read_b128 v[142:145], v3 offset:2048
	ds_read_b128 v[146:149], v3 offset:3072
	s_waitcnt lgkmcnt(0)
	ds_read_b128 v[190:193], v250 offset:32768
	ds_read_b128 v[194:197], v250 offset:33792
	ds_read_b128 v[182:185], v250 offset:34816
	ds_read_b128 v[186:189], v250 offset:35840
	ds_read_b128 v[174:177], v250 offset:36864
	ds_read_b128 v[178:181], v250 offset:37888
	ds_read_b128 v[166:169], v250 offset:38912
	ds_read_b128 v[170:173], v250 offset:39936
	s_add_u32 s84, s84, 0x40000
	s_addc_u32 s85, s85, 0
	s_mov_b32 m0, s95
	v_lshl_add_u64 v[252:253], s[84:85], 0, v[206:207]
	global_load_lds_dwordx4 v[252:253], off
	v_lshl_add_u64 v[252:253], s[84:85], 0, v[210:211]
	s_mov_b32 m0, s96
	s_nop 0
	global_load_lds_dwordx4 v[252:253], off
	s_waitcnt vmcnt(8)
.LBB0_117:
	s_waitcnt lgkmcnt(0)
	s_setprio 1
	s_barrier
	v_mfma_f32_16x16x32_bf16 v[102:105], v[150:153], v[190:193], v[102:105]
	v_mfma_f32_16x16x32_bf16 v[70:73], v[158:161], v[190:193], v[70:73]
	v_mfma_f32_16x16x32_bf16 v[114:117], v[150:153], v[182:185], v[114:117]
	v_mfma_f32_16x16x32_bf16 v[82:85], v[158:161], v[182:185], v[82:85]
	v_mfma_f32_16x16x32_bf16 v[110:113], v[150:153], v[174:177], v[110:113]
	v_mfma_f32_16x16x32_bf16 v[78:81], v[158:161], v[174:177], v[78:81]
	v_mfma_f32_16x16x32_bf16 v[106:109], v[150:153], v[166:169], v[106:109]
	v_mfma_f32_16x16x32_bf16 v[74:77], v[158:161], v[166:169], v[74:77]
	v_mfma_f32_16x16x32_bf16 v[102:105], v[154:157], v[194:197], v[102:105]
	v_mfma_f32_16x16x32_bf16 v[70:73], v[162:165], v[194:197], v[70:73]
	v_mfma_f32_16x16x32_bf16 v[114:117], v[154:157], v[186:189], v[114:117]
	v_mfma_f32_16x16x32_bf16 v[82:85], v[162:165], v[186:189], v[82:85]
	v_mfma_f32_16x16x32_bf16 v[110:113], v[154:157], v[178:181], v[110:113]
	v_mfma_f32_16x16x32_bf16 v[78:81], v[162:165], v[178:181], v[78:81]
	v_mfma_f32_16x16x32_bf16 v[106:109], v[154:157], v[170:173], v[106:109]
	v_mfma_f32_16x16x32_bf16 v[74:77], v[162:165], v[170:173], v[74:77]
	v_mfma_f32_16x16x32_bf16 v[130:133], v[134:137], v[190:193], v[130:133]
	v_mfma_f32_16x16x32_bf16 v[98:101], v[142:145], v[190:193], v[98:101]
	v_mfma_f32_16x16x32_bf16 v[126:129], v[134:137], v[182:185], v[126:129]
	v_mfma_f32_16x16x32_bf16 v[94:97], v[142:145], v[182:185], v[94:97]
	v_mfma_f32_16x16x32_bf16 v[122:125], v[134:137], v[174:177], v[122:125]
	v_mfma_f32_16x16x32_bf16 v[90:93], v[142:145], v[174:177], v[90:93]
	v_mfma_f32_16x16x32_bf16 v[118:121], v[134:137], v[166:169], v[118:121]
	v_mfma_f32_16x16x32_bf16 v[86:89], v[142:145], v[166:169], v[86:89]
	v_mfma_f32_16x16x32_bf16 v[130:133], v[138:141], v[194:197], v[130:133]
	v_mfma_f32_16x16x32_bf16 v[98:101], v[146:149], v[194:197], v[98:101]
	v_mfma_f32_16x16x32_bf16 v[126:129], v[138:141], v[186:189], v[126:129]
	v_mfma_f32_16x16x32_bf16 v[94:97], v[146:149], v[186:189], v[94:97]
	v_mfma_f32_16x16x32_bf16 v[122:125], v[138:141], v[178:181], v[122:125]
	v_mfma_f32_16x16x32_bf16 v[90:93], v[146:149], v[178:181], v[90:93]
	v_mfma_f32_16x16x32_bf16 v[118:121], v[138:141], v[170:173], v[118:121]
	v_mfma_f32_16x16x32_bf16 v[86:89], v[146:149], v[170:173], v[86:89]
	s_setprio 0
	s_barrier
	ds_read_b128 v[190:193], v250 offset:49152
	ds_read_b128 v[194:197], v250 offset:50176
	ds_read_b128 v[182:185], v250 offset:51200
	ds_read_b128 v[186:189], v250 offset:52224
	ds_read_b128 v[174:177], v250 offset:53248
	ds_read_b128 v[178:181], v250 offset:54272
	ds_read_b128 v[166:169], v250 offset:55296
	ds_read_b128 v[170:173], v250 offset:56320
	s_mov_b32 m0, s54
	v_lshl_add_u64 v[224:225], v[224:225], 0, s[12:13]
	s_add_u32 s2, s2, 0x40080
	global_load_lds_dwordx4 v[224:225], off
	v_lshl_add_u64 v[222:223], v[222:223], 0, s[12:13]
	s_mov_b32 m0, s55
	s_addc_u32 s3, s3, 0
	global_load_lds_dwordx4 v[222:223], off
	v_lshl_add_u64 v[222:223], s[2:3], 0, v[208:209]
	s_mov_b32 m0, s59
	v_lshl_add_u64 v[220:221], v[220:221], 0, s[12:13]
	global_load_lds_dwordx4 v[222:223], off
	v_lshl_add_u64 v[222:223], s[2:3], 0, v[212:213]
	s_mov_b32 m0, s24
	v_lshl_add_u64 v[4:5], v[4:5], 0, s[12:13]
	global_load_lds_dwordx4 v[222:223], off
	s_mov_b32 m0, s57
	s_nop 0
	global_load_lds_dwordx4 v[220:221], off
	s_mov_b32 m0, s58
	s_nop 0
	global_load_lds_dwordx4 v[4:5], off
	s_waitcnt vmcnt(8)

.LBB0_106:
	s_barrier
	s_add_i32 s45, s45, 2
	s_add_u32 s36, s36, 0x100
	s_addc_u32 s44, s44, 0
	s_cmp_gt_u32 s45, 13
	s_cbranch_scc0 .LBB0_107
	s_mov_b64 s[0:1], 0
